# P2 compress k-loop: 4 rotating register sets keep three 8-load steps in flight (on top of the vectorized V re-layout)
# speedup vs baseline: 1.0068x; 1.0027x over previous
.LBB0_391:
	v_min_u32_e32 v0, 0x7fff, v19
	v_mul_u32_u24_e32 v0, 0xe00, v0
	v_lshlrev_b32_e32 v0, 1, v0
	v_lshl_add_u64 v[58:59], v[20:21], 0, v[0:1]
	global_load_dwordx4 v[76:79], v[22:23], off offset:-128
	global_load_dwordx4 v[108:111], v[58:59], off
	global_load_dwordx4 v[80:83], v[22:23], off offset:-96
	global_load_dwordx4 v[112:115], v[58:59], off offset:32
	global_load_dwordx4 v[84:87], v[22:23], off offset:-64
	global_load_dwordx4 v[116:119], v[58:59], off offset:64
	global_load_dwordx4 v[88:91], v[22:23], off offset:-32
	global_load_dwordx4 v[120:123], v[58:59], off offset:96
	v_add_u32_e32 v19, 1, v19
	v_min_u32_e32 v0, 0x7fff, v19
	v_mul_u32_u24_e32 v0, 0xe00, v0
	v_lshlrev_b32_e32 v0, 1, v0
	v_lshl_add_u64 v[58:59], v[20:21], 0, v[0:1]
	global_load_dwordx4 v[92:95], v[22:23], off
	global_load_dwordx4 v[124:127], v[58:59], off
	global_load_dwordx4 v[96:99], v[22:23], off offset:32
	global_load_dwordx4 v[128:131], v[58:59], off offset:32
	global_load_dwordx4 v[100:103], v[22:23], off offset:64
	global_load_dwordx4 v[132:135], v[58:59], off offset:64
	global_load_dwordx4 v[104:107], v[22:23], off offset:96
	global_load_dwordx4 v[136:139], v[58:59], off offset:96
	v_add_u32_e32 v19, 1, v19
	v_lshl_add_u64 v[22:23], v[22:23], 0, s[88:89]
	v_min_u32_e32 v0, 0x7fff, v19
	v_mul_u32_u24_e32 v0, 0xe00, v0
	v_lshlrev_b32_e32 v0, 1, v0
	v_lshl_add_u64 v[58:59], v[20:21], 0, v[0:1]
	global_load_dwordx4 v[140:143], v[22:23], off offset:-128
	global_load_dwordx4 v[172:175], v[58:59], off
	global_load_dwordx4 v[144:147], v[22:23], off offset:-96
	global_load_dwordx4 v[176:179], v[58:59], off offset:32
	global_load_dwordx4 v[148:151], v[22:23], off offset:-64
	global_load_dwordx4 v[180:183], v[58:59], off offset:64
	global_load_dwordx4 v[152:155], v[22:23], off offset:-32
	global_load_dwordx4 v[184:187], v[58:59], off offset:96
	v_add_u32_e32 v19, 1, v19
	s_mov_b32 s37, 7
.Lcmp_loop:
	v_min_u32_e32 v0, 0x7fff, v19
	v_mul_u32_u24_e32 v0, 0xe00, v0
	v_lshlrev_b32_e32 v0, 1, v0
	v_lshl_add_u64 v[58:59], v[20:21], 0, v[0:1]
	global_load_dwordx4 v[156:159], v[22:23], off
	global_load_dwordx4 v[188:191], v[58:59], off
	global_load_dwordx4 v[160:163], v[22:23], off offset:32
	global_load_dwordx4 v[220:223], v[58:59], off offset:32
	global_load_dwordx4 v[164:167], v[22:23], off offset:64
	global_load_dwordx4 v[224:227], v[58:59], off offset:64
	global_load_dwordx4 v[168:171], v[22:23], off offset:96
	global_load_dwordx4 v[228:231], v[58:59], off offset:96
	v_add_u32_e32 v19, 1, v19
	v_lshl_add_u64 v[22:23], v[22:23], 0, s[88:89]
	s_waitcnt vmcnt(24)
	v_mfma_f32_32x32x16_bf16 v[2:17], v[76:79], v[108:111], v[2:17]
	v_mfma_f32_32x32x16_bf16 v[2:17], v[80:83], v[112:115], v[2:17]
	v_mfma_f32_32x32x16_bf16 v[2:17], v[84:87], v[116:119], v[2:17]
	v_mfma_f32_32x32x16_bf16 v[2:17], v[88:91], v[120:123], v[2:17]
	v_min_u32_e32 v0, 0x7fff, v19
	v_mul_u32_u24_e32 v0, 0xe00, v0
	v_lshlrev_b32_e32 v0, 1, v0
	v_lshl_add_u64 v[58:59], v[20:21], 0, v[0:1]
	global_load_dwordx4 v[76:79], v[22:23], off offset:-128
	global_load_dwordx4 v[108:111], v[58:59], off
	global_load_dwordx4 v[80:83], v[22:23], off offset:-96
	global_load_dwordx4 v[112:115], v[58:59], off offset:32
	global_load_dwordx4 v[84:87], v[22:23], off offset:-64
	global_load_dwordx4 v[116:119], v[58:59], off offset:64
	global_load_dwordx4 v[88:91], v[22:23], off offset:-32
	global_load_dwordx4 v[120:123], v[58:59], off offset:96
	v_add_u32_e32 v19, 1, v19
	s_waitcnt vmcnt(24)
	v_mfma_f32_32x32x16_bf16 v[2:17], v[92:95], v[124:127], v[2:17]
	v_mfma_f32_32x32x16_bf16 v[2:17], v[96:99], v[128:131], v[2:17]
	v_mfma_f32_32x32x16_bf16 v[2:17], v[100:103], v[132:135], v[2:17]
	v_mfma_f32_32x32x16_bf16 v[2:17], v[104:107], v[136:139], v[2:17]
	v_min_u32_e32 v0, 0x7fff, v19
	v_mul_u32_u24_e32 v0, 0xe00, v0
	v_lshlrev_b32_e32 v0, 1, v0
	v_lshl_add_u64 v[58:59], v[20:21], 0, v[0:1]
	global_load_dwordx4 v[92:95], v[22:23], off
	global_load_dwordx4 v[124:127], v[58:59], off
	global_load_dwordx4 v[96:99], v[22:23], off offset:32
	global_load_dwordx4 v[128:131], v[58:59], off offset:32
	global_load_dwordx4 v[100:103], v[22:23], off offset:64
	global_load_dwordx4 v[132:135], v[58:59], off offset:64
	global_load_dwordx4 v[104:107], v[22:23], off offset:96
	global_load_dwordx4 v[136:139], v[58:59], off offset:96
	v_add_u32_e32 v19, 1, v19
	v_lshl_add_u64 v[22:23], v[22:23], 0, s[88:89]
	s_waitcnt vmcnt(24)
	v_mfma_f32_32x32x16_bf16 v[2:17], v[140:143], v[172:175], v[2:17]
	v_mfma_f32_32x32x16_bf16 v[2:17], v[144:147], v[176:179], v[2:17]
	v_mfma_f32_32x32x16_bf16 v[2:17], v[148:151], v[180:183], v[2:17]
	v_mfma_f32_32x32x16_bf16 v[2:17], v[152:155], v[184:187], v[2:17]
	v_min_u32_e32 v0, 0x7fff, v19
	v_mul_u32_u24_e32 v0, 0xe00, v0
	v_lshlrev_b32_e32 v0, 1, v0
	v_lshl_add_u64 v[58:59], v[20:21], 0, v[0:1]
	global_load_dwordx4 v[140:143], v[22:23], off offset:-128
	global_load_dwordx4 v[172:175], v[58:59], off
	global_load_dwordx4 v[144:147], v[22:23], off offset:-96
	global_load_dwordx4 v[176:179], v[58:59], off offset:32
	global_load_dwordx4 v[148:151], v[22:23], off offset:-64
	global_load_dwordx4 v[180:183], v[58:59], off offset:64
	global_load_dwordx4 v[152:155], v[22:23], off offset:-32
	global_load_dwordx4 v[184:187], v[58:59], off offset:96
	v_add_u32_e32 v19, 1, v19
	s_waitcnt vmcnt(24)
	v_mfma_f32_32x32x16_bf16 v[2:17], v[156:159], v[188:191], v[2:17]
	v_mfma_f32_32x32x16_bf16 v[2:17], v[160:163], v[220:223], v[2:17]
	v_mfma_f32_32x32x16_bf16 v[2:17], v[164:167], v[224:227], v[2:17]
	v_mfma_f32_32x32x16_bf16 v[2:17], v[168:171], v[228:231], v[2:17]
	s_sub_u32 s37, s37, 1
	s_cmp_lg_u32 s37, 0
	s_cbranch_scc1 .Lcmp_loop
	v_min_u32_e32 v0, 0x7fff, v19
	v_mul_u32_u24_e32 v0, 0xe00, v0
	v_lshlrev_b32_e32 v0, 1, v0
	v_lshl_add_u64 v[58:59], v[20:21], 0, v[0:1]
	global_load_dwordx4 v[156:159], v[22:23], off
	global_load_dwordx4 v[188:191], v[58:59], off
	global_load_dwordx4 v[160:163], v[22:23], off offset:32
	global_load_dwordx4 v[220:223], v[58:59], off offset:32
	global_load_dwordx4 v[164:167], v[22:23], off offset:64
	global_load_dwordx4 v[224:227], v[58:59], off offset:64
	global_load_dwordx4 v[168:171], v[22:23], off offset:96
	global_load_dwordx4 v[228:231], v[58:59], off offset:96
	v_add_u32_e32 v19, 1, v19
	v_lshl_add_u64 v[22:23], v[22:23], 0, s[88:89]
	s_waitcnt vmcnt(24)
	v_mfma_f32_32x32x16_bf16 v[2:17], v[76:79], v[108:111], v[2:17]
	v_mfma_f32_32x32x16_bf16 v[2:17], v[80:83], v[112:115], v[2:17]
	v_mfma_f32_32x32x16_bf16 v[2:17], v[84:87], v[116:119], v[2:17]
	v_mfma_f32_32x32x16_bf16 v[2:17], v[88:91], v[120:123], v[2:17]
	s_waitcnt vmcnt(16)
	v_mfma_f32_32x32x16_bf16 v[2:17], v[92:95], v[124:127], v[2:17]
	v_mfma_f32_32x32x16_bf16 v[2:17], v[96:99], v[128:131], v[2:17]
	v_mfma_f32_32x32x16_bf16 v[2:17], v[100:103], v[132:135], v[2:17]
	v_mfma_f32_32x32x16_bf16 v[2:17], v[104:107], v[136:139], v[2:17]
	s_waitcnt vmcnt(8)
	v_mfma_f32_32x32x16_bf16 v[2:17], v[140:143], v[172:175], v[2:17]
	v_mfma_f32_32x32x16_bf16 v[2:17], v[144:147], v[176:179], v[2:17]
	v_mfma_f32_32x32x16_bf16 v[2:17], v[148:151], v[180:183], v[2:17]
	v_mfma_f32_32x32x16_bf16 v[2:17], v[152:155], v[184:187], v[2:17]
	s_waitcnt vmcnt(0)
	v_mfma_f32_32x32x16_bf16 v[2:17], v[156:159], v[188:191], v[2:17]
	v_mfma_f32_32x32x16_bf16 v[2:17], v[160:163], v[220:223], v[2:17]
	v_mfma_f32_32x32x16_bf16 v[2:17], v[164:167], v[224:227], v[2:17]
	v_mfma_f32_32x32x16_bf16 v[2:17], v[168:171], v[228:231], v[2:17]
	s_movk_i32 s37, 0x78
	s_add_i32 s36, s36, s30
	s_lshl_b32 s38, s36, 7
	s_ashr_i32 s39, s38, 31
	v_readlane_b32 s44, v252, 34
	s_lshl_b64 s[38:39], s[38:39], 2
	v_readlane_b32 s54, v252, 44
	v_readlane_b32 s55, v252, 45
	s_add_u32 s38, s54, s38
	s_addc_u32 s39, s55, s39
	v_ashrrev_i32_e32 v67, 31, v66
	v_lshl_add_u64 v[20:21], v[66:67], 2, s[38:39]
	v_mov_b32_e32 v19, v1
	v_lshl_add_u64 v[18:19], v[20:21], 0, v[18:19]
	v_lshlrev_b32_e32 v0, 11, v75
	v_lshlrev_b32_e32 v20, 4, v74
	v_add3_u32 v0, 0, v0, v20
	global_load_dwordx4 v[20:23], v[18:19], off
	v_mov_b32_e32 v27, v4
	v_mov_b32_e32 v4, v3
	v_mov_b32_e32 v26, v2
	v_readlane_b32 s45, v252, 35
	v_readlane_b32 s46, v252, 36
	v_readlane_b32 s47, v252, 37
	v_readlane_b32 s48, v252, 38
	v_readlane_b32 s49, v252, 39
	v_readlane_b32 s50, v252, 40
	v_readlane_b32 s51, v252, 41
	v_readlane_b32 s52, v252, 42
	v_readlane_b32 s53, v252, 43
	v_readlane_b32 s56, v252, 46
	v_readlane_b32 s57, v252, 47
	v_readlane_b32 s58, v252, 48
	v_readlane_b32 s59, v252, 49
	s_waitcnt vmcnt(0)
	v_mov_b32_e32 v29, v22
	v_mov_b32_e32 v22, v21
	v_mov_b32_e32 v28, v20
	v_pk_add_f32 v[4:5], v[4:5], v[22:23]
	v_pk_add_f32 v[26:27], v[26:27], v[28:29]
	v_mul_f32_e32 v3, 0xbfb8aa3b, v4
	v_mul_f32_e32 v2, 0xbfb8aa3b, v26
	v_exp_f32_e32 v20, v3
	v_mul_f32_e32 v3, 0xbfb8aa3b, v27
	v_exp_f32_e32 v2, v2
	v_exp_f32_e32 v3, v3
	s_nop 0
	v_pk_add_f32 v[2:3], v[2:3], 1.0 op_sel_hi:[1,0]
	s_nop 0
	v_div_scale_f32 v21, s[38:39], v3, v3, v27
	v_rcp_f32_e32 v22, v21
	s_nop 0
	v_fma_f32 v23, -v21, v22, 1.0
	v_fmac_f32_e32 v22, v23, v22
	v_div_scale_f32 v23, vcc, v27, v3, v27
	v_mul_f32_e32 v25, v23, v22
	v_fma_f32 v28, -v21, v25, v23
	v_fmac_f32_e32 v25, v28, v22
	v_fma_f32 v21, -v21, v25, v23
	v_div_fmas_f32 v21, v21, v22, v25
	v_div_fixup_f32 v22, v21, v3, v27
	v_div_scale_f32 v3, s[38:39], v2, v2, v26
	v_rcp_f32_e32 v21, v3
	s_nop 0
	v_fma_f32 v23, -v3, v21, 1.0
	v_fmac_f32_e32 v21, v23, v21
	v_div_scale_f32 v23, vcc, v26, v2, v26
	v_mul_f32_e32 v25, v23, v21
	v_fma_f32 v27, -v3, v25, v23
	v_fmac_f32_e32 v25, v27, v21
	v_fma_f32 v3, -v3, v25, v23
	v_div_fmas_f32 v3, v3, v21, v25
	v_div_fixup_f32 v23, v3, v2, v26
	v_mul_f32_e32 v2, 0xbfb8aa3b, v5
	v_exp_f32_e32 v21, v2
	s_nop 0
	v_pk_add_f32 v[2:3], v[20:21], 1.0 op_sel_hi:[1,0]
	s_nop 0
	v_div_scale_f32 v20, s[38:39], v3, v3, v5
	v_rcp_f32_e32 v21, v20
	s_nop 0
	v_fma_f32 v25, -v20, v21, 1.0
	v_fmac_f32_e32 v21, v25, v21
	v_div_scale_f32 v25, vcc, v5, v3, v5
	v_mul_f32_e32 v26, v25, v21
	v_fma_f32 v27, -v20, v26, v25
	v_fmac_f32_e32 v26, v27, v21
	v_fma_f32 v20, -v20, v26, v25
	v_div_fmas_f32 v20, v20, v21, v26
	v_div_fixup_f32 v3, v20, v3, v5
	v_div_scale_f32 v5, s[38:39], v2, v2, v4
	v_rcp_f32_e32 v20, v5
	s_nop 0
	v_fma_f32 v21, -v5, v20, 1.0
	v_fmac_f32_e32 v20, v21, v20
	v_div_scale_f32 v21, vcc, v4, v2, v4
	v_mul_f32_e32 v25, v21, v20
	v_fma_f32 v26, -v5, v25, v21
	v_fmac_f32_e32 v25, v26, v20
	v_fma_f32 v5, -v5, v25, v21
	v_div_fmas_f32 v5, v5, v20, v25
	v_div_fixup_f32 v2, v5, v2, v4
	v_cvt_pk_bf16_f32 v4, v23, v22
	global_load_dwordx4 v[20:23], v[18:19], off offset:32
	v_cvt_pk_bf16_f32 v2, v2, v3
	v_and_b32_e32 v3, 0xffff0000, v2
	v_lshlrev_b32_e32 v2, 16, v2
	v_mov_b32_e32 v5, v8
	v_mov_b32_e32 v8, v7
	v_or_b32_sdwa v3, v3, v4 dst_sel:DWORD dst_unused:UNUSED_PAD src0_sel:DWORD src1_sel:WORD_1
	v_or_b32_sdwa v2, v2, v4 dst_sel:DWORD dst_unused:UNUSED_PAD src0_sel:DWORD src1_sel:WORD_0
	v_mov_b32_e32 v4, v6
	s_waitcnt vmcnt(0)
	v_mov_b32_e32 v27, v22
	v_mov_b32_e32 v22, v21
	v_mov_b32_e32 v26, v20
	v_pk_add_f32 v[8:9], v[8:9], v[22:23]
	v_pk_add_f32 v[4:5], v[4:5], v[26:27]
	v_mul_f32_e32 v7, 0xbfb8aa3b, v8
	v_mul_f32_e32 v6, 0xbfb8aa3b, v4
	v_exp_f32_e32 v20, v7
	v_mul_f32_e32 v7, 0xbfb8aa3b, v5
	v_exp_f32_e32 v6, v6
	v_exp_f32_e32 v7, v7
	s_nop 0
	v_pk_add_f32 v[6:7], v[6:7], 1.0 op_sel_hi:[1,0]
	s_nop 0
	v_div_scale_f32 v21, s[38:39], v7, v7, v5
	v_rcp_f32_e32 v22, v21
	s_nop 0
	v_fma_f32 v23, -v21, v22, 1.0
	v_fmac_f32_e32 v22, v23, v22
	v_div_scale_f32 v23, vcc, v5, v7, v5
	v_mul_f32_e32 v25, v23, v22
	v_fma_f32 v26, -v21, v25, v23
	v_fmac_f32_e32 v25, v26, v22
	v_fma_f32 v21, -v21, v25, v23
	v_div_fmas_f32 v21, v21, v22, v25
	v_div_fixup_f32 v7, v21, v7, v5
	v_div_scale_f32 v5, s[38:39], v6, v6, v4
	v_rcp_f32_e32 v21, v5
	s_nop 0
	v_fma_f32 v22, -v5, v21, 1.0
	v_fmac_f32_e32 v21, v22, v21
	v_div_scale_f32 v22, vcc, v4, v6, v4
	v_mul_f32_e32 v23, v22, v21
	v_fma_f32 v25, -v5, v23, v22
	v_fmac_f32_e32 v23, v25, v21
	v_fma_f32 v5, -v5, v23, v22
	v_div_fmas_f32 v5, v5, v21, v23
	v_div_fixup_f32 v6, v5, v6, v4
	v_mul_f32_e32 v4, 0xbfb8aa3b, v9
	v_exp_f32_e32 v21, v4
	v_cvt_pk_bf16_f32 v6, v6, v7
	v_mov_b32_e32 v7, v12
	v_mov_b32_e32 v12, v11
	v_pk_add_f32 v[4:5], v[20:21], 1.0 op_sel_hi:[1,0]
	s_nop 0
	v_div_scale_f32 v20, s[38:39], v5, v5, v9
	v_rcp_f32_e32 v21, v20
	s_nop 0
	v_fma_f32 v22, -v20, v21, 1.0
	v_fmac_f32_e32 v21, v22, v21
	v_div_scale_f32 v22, vcc, v9, v5, v9
	v_mul_f32_e32 v23, v22, v21
	v_fma_f32 v25, -v20, v23, v22
	v_fmac_f32_e32 v23, v25, v21
	v_fma_f32 v20, -v20, v23, v22
	v_div_fmas_f32 v20, v20, v21, v23
	v_div_fixup_f32 v5, v20, v5, v9
	v_div_scale_f32 v9, s[38:39], v4, v4, v8
	v_rcp_f32_e32 v20, v9
	s_nop 0
	v_fma_f32 v21, -v9, v20, 1.0
	v_fmac_f32_e32 v20, v21, v20
	v_div_scale_f32 v21, vcc, v8, v4, v8
	v_mul_f32_e32 v22, v21, v20
	v_fma_f32 v23, -v9, v22, v21
	v_fmac_f32_e32 v22, v23, v20
	v_fma_f32 v9, -v9, v22, v21
	v_div_fmas_f32 v9, v9, v20, v22
	v_div_fixup_f32 v4, v9, v4, v8
	v_cvt_pk_bf16_f32 v4, v4, v5
	v_and_b32_e32 v5, 0xffff0000, v4
	v_lshlrev_b32_e32 v4, 16, v4
	v_or_b32_sdwa v5, v5, v6 dst_sel:DWORD dst_unused:UNUSED_PAD src0_sel:DWORD src1_sel:WORD_1
	v_or_b32_sdwa v4, v4, v6 dst_sel:DWORD dst_unused:UNUSED_PAD src0_sel:DWORD src1_sel:WORD_0
	ds_write_b128 v0, v[2:5]
	global_load_dwordx4 v[2:5], v[18:19], off offset:64
	v_mov_b32_e32 v6, v10
	s_waitcnt vmcnt(0)
	v_mov_b32_e32 v9, v4
	v_mov_b32_e32 v4, v3
	v_mov_b32_e32 v8, v2
	v_pk_add_f32 v[4:5], v[12:13], v[4:5]
	v_pk_add_f32 v[6:7], v[6:7], v[8:9]
	v_mul_f32_e32 v3, 0xbfb8aa3b, v4
	v_mul_f32_e32 v2, 0xbfb8aa3b, v6
	v_exp_f32_e32 v8, v3
	v_mul_f32_e32 v3, 0xbfb8aa3b, v7
	v_exp_f32_e32 v2, v2
	v_exp_f32_e32 v3, v3
	s_nop 0
	v_pk_add_f32 v[2:3], v[2:3], 1.0 op_sel_hi:[1,0]
	s_nop 0
	v_div_scale_f32 v9, s[38:39], v3, v3, v7
	v_rcp_f32_e32 v10, v9
	s_nop 0
	v_fma_f32 v11, -v9, v10, 1.0
	v_fmac_f32_e32 v10, v11, v10
	v_div_scale_f32 v11, vcc, v7, v3, v7
	v_mul_f32_e32 v12, v11, v10
	v_fma_f32 v13, -v9, v12, v11
	v_fmac_f32_e32 v12, v13, v10
	v_fma_f32 v9, -v9, v12, v11
	v_div_fmas_f32 v9, v9, v10, v12
	v_div_fixup_f32 v7, v9, v3, v7
	v_div_scale_f32 v3, s[38:39], v2, v2, v6
	v_rcp_f32_e32 v9, v3
	s_nop 0
	v_fma_f32 v10, -v3, v9, 1.0
	v_fmac_f32_e32 v9, v10, v9
	v_div_scale_f32 v10, vcc, v6, v2, v6
	v_mul_f32_e32 v11, v10, v9
	v_fma_f32 v12, -v3, v11, v10
	v_fmac_f32_e32 v11, v12, v9
	v_fma_f32 v3, -v3, v11, v10
	v_div_fmas_f32 v3, v3, v9, v11
	v_div_fixup_f32 v6, v3, v2, v6
	v_mul_f32_e32 v2, 0xbfb8aa3b, v5
	v_exp_f32_e32 v9, v2
	s_nop 0
	v_pk_add_f32 v[2:3], v[8:9], 1.0 op_sel_hi:[1,0]
	s_nop 0
	v_div_scale_f32 v8, s[38:39], v3, v3, v5
	v_rcp_f32_e32 v9, v8
	s_nop 0
	v_fma_f32 v10, -v8, v9, 1.0
	v_fmac_f32_e32 v9, v10, v9
	v_div_scale_f32 v10, vcc, v5, v3, v5
	v_mul_f32_e32 v11, v10, v9
	v_fma_f32 v12, -v8, v11, v10
	v_fmac_f32_e32 v11, v12, v9
	v_fma_f32 v8, -v8, v11, v10
	v_div_fmas_f32 v8, v8, v9, v11
	v_div_fixup_f32 v3, v8, v3, v5
	v_div_scale_f32 v5, s[38:39], v2, v2, v4
	v_rcp_f32_e32 v8, v5
	s_nop 0
	v_fma_f32 v9, -v5, v8, 1.0
	v_fmac_f32_e32 v8, v9, v8
	v_div_scale_f32 v9, vcc, v4, v2, v4
	v_mul_f32_e32 v10, v9, v8
	v_fma_f32 v11, -v5, v10, v9
	v_fmac_f32_e32 v10, v11, v8
	v_fma_f32 v5, -v5, v10, v9
	v_div_fmas_f32 v5, v5, v8, v10
	v_div_fixup_f32 v2, v5, v2, v4
	v_cvt_pk_bf16_f32 v2, v2, v3
	v_cvt_pk_bf16_f32 v4, v6, v7
	v_and_b32_e32 v3, 0xffff0000, v2
	v_lshlrev_b32_e32 v2, 16, v2
	v_or_b32_sdwa v3, v3, v4 dst_sel:DWORD dst_unused:UNUSED_PAD src0_sel:DWORD src1_sel:WORD_1
	v_or_b32_sdwa v2, v2, v4 dst_sel:DWORD dst_unused:UNUSED_PAD src0_sel:DWORD src1_sel:WORD_0
	global_load_dwordx4 v[4:7], v[18:19], off offset:96
	v_mov_b32_e32 v9, v16
	v_mov_b32_e32 v16, v15
	v_mov_b32_e32 v8, v14
	s_waitcnt vmcnt(0)
	v_mov_b32_e32 v11, v6
	v_mov_b32_e32 v6, v5
	v_mov_b32_e32 v10, v4
	v_pk_add_f32 v[6:7], v[16:17], v[6:7]
	v_pk_add_f32 v[8:9], v[8:9], v[10:11]
	v_mul_f32_e32 v5, 0xbfb8aa3b, v6
	v_mul_f32_e32 v4, 0xbfb8aa3b, v8
	v_exp_f32_e32 v10, v5
	v_mul_f32_e32 v5, 0xbfb8aa3b, v9
	v_exp_f32_e32 v4, v4
	v_exp_f32_e32 v5, v5
	s_nop 0
	v_pk_add_f32 v[4:5], v[4:5], 1.0 op_sel_hi:[1,0]
	s_nop 0
	v_div_scale_f32 v11, s[38:39], v5, v5, v9
	v_rcp_f32_e32 v12, v11
	s_nop 0
	v_fma_f32 v13, -v11, v12, 1.0
	v_fmac_f32_e32 v12, v13, v12
	v_div_scale_f32 v13, vcc, v9, v5, v9
	v_mul_f32_e32 v14, v13, v12
	v_fma_f32 v15, -v11, v14, v13
	v_fmac_f32_e32 v14, v15, v12
	v_fma_f32 v11, -v11, v14, v13
	v_div_fmas_f32 v11, v11, v12, v14
	v_div_fixup_f32 v9, v11, v5, v9
	v_div_scale_f32 v5, s[38:39], v4, v4, v8
	v_rcp_f32_e32 v11, v5
	s_nop 0
	v_fma_f32 v12, -v5, v11, 1.0
	v_fmac_f32_e32 v11, v12, v11
	v_div_scale_f32 v12, vcc, v8, v4, v8
	v_mul_f32_e32 v13, v12, v11
	v_fma_f32 v14, -v5, v13, v12
	v_fmac_f32_e32 v13, v14, v11
	v_fma_f32 v5, -v5, v13, v12
	v_div_fmas_f32 v5, v5, v11, v13
	v_div_fixup_f32 v8, v5, v4, v8
	v_mul_f32_e32 v4, 0xbfb8aa3b, v7
	v_exp_f32_e32 v11, v4
	s_nop 0
	v_pk_add_f32 v[4:5], v[10:11], 1.0 op_sel_hi:[1,0]
	s_nop 0
	v_div_scale_f32 v10, s[38:39], v5, v5, v7
	v_rcp_f32_e32 v11, v10
	s_nop 0
	v_fma_f32 v12, -v10, v11, 1.0
	v_fmac_f32_e32 v11, v12, v11
	v_div_scale_f32 v12, vcc, v7, v5, v7
	v_mul_f32_e32 v13, v12, v11
	v_fma_f32 v14, -v10, v13, v12
	v_fmac_f32_e32 v13, v14, v11
	v_fma_f32 v10, -v10, v13, v12
	v_div_fmas_f32 v10, v10, v11, v13
	v_div_fixup_f32 v5, v10, v5, v7
	v_div_scale_f32 v7, s[38:39], v4, v4, v6
	v_rcp_f32_e32 v10, v7
	s_nop 0
	v_fma_f32 v11, -v7, v10, 1.0
	v_fmac_f32_e32 v10, v11, v10
	v_div_scale_f32 v11, vcc, v6, v4, v6
	v_mul_f32_e32 v12, v11, v10
	v_fma_f32 v13, -v7, v12, v11
	v_fmac_f32_e32 v12, v13, v10
	v_fma_f32 v7, -v7, v12, v11
	v_div_fmas_f32 v7, v7, v10, v12
	v_div_fixup_f32 v4, v7, v4, v6
	v_cvt_pk_bf16_f32 v4, v4, v5
	v_cvt_pk_bf16_f32 v6, v8, v9
	v_and_b32_e32 v5, 0xffff0000, v4
	v_lshlrev_b32_e32 v4, 16, v4
	v_or_b32_sdwa v5, v5, v6 dst_sel:DWORD dst_unused:UNUSED_PAD src0_sel:DWORD src1_sel:WORD_1
	v_or_b32_sdwa v4, v4, v6 dst_sel:DWORD dst_unused:UNUSED_PAD src0_sel:DWORD src1_sel:WORD_0
	v_cmp_gt_i32_e32 vcc, 2, v75
	ds_write_b128 v0, v[2:5] offset:1024
	s_waitcnt lgkmcnt(0)
	s_barrier
	s_and_saveexec_b64 s[38:39], vcc
	s_cbranch_execz .LBB0_315
	v_lshl_add_u32 v2, s36, 6, v66
	v_or_b32_e32 v2, v2, v73
	v_ashrrev_i32_e32 v3, 31, v2
	v_readlane_b32 s44, v252, 34
	v_lshlrev_b32_e32 v0, 2, v24
	v_lshlrev_b64 v[2:3], 8, v[2:3]
	v_readlane_b32 s52, v252, 42
	v_readlane_b32 s53, v252, 43
	v_lshlrev_b32_e32 v0, 1, v0
	v_lshl_add_u32 v76, v74, 4, 0
	v_lshl_add_u64 v[2:3], s[52:53], 0, v[2:3]
	v_lshl_add_u64 v[2:3], v[2:3], 0, v[0:1]
	global_load_dwordx2 v[18:19], v[2:3], off
	global_load_dwordx2 v[20:21], v[2:3], off offset:16
	global_load_dwordx2 v[58:59], v[2:3], off offset:32
	global_load_dwordx2 v[60:61], v[2:3], off offset:48
	global_load_dwordx2 v[54:55], v[2:3], off offset:64
	global_load_dwordx2 v[56:57], v[2:3], off offset:80
	global_load_dwordx2 v[50:51], v[2:3], off offset:96
	global_load_dwordx2 v[52:53], v[2:3], off offset:112
	global_load_dwordx2 v[46:47], v[2:3], off offset:128
	global_load_dwordx2 v[48:49], v[2:3], off offset:144
	global_load_dwordx2 v[42:43], v[2:3], off offset:160
	global_load_dwordx2 v[44:45], v[2:3], off offset:176
	global_load_dwordx2 v[38:39], v[2:3], off offset:192
	global_load_dwordx2 v[40:41], v[2:3], off offset:208
	global_load_dwordx2 v[34:35], v[2:3], off offset:224
	global_load_dwordx2 v[36:37], v[2:3], off offset:240
	ds_read_b128 v[22:25], v76
	s_mov_b64 s[36:37], -1
	s_and_b64 vcc, exec, s[0:1]
	v_readlane_b32 s45, v252, 35
	v_readlane_b32 s46, v252, 36
	v_readlane_b32 s47, v252, 37
	v_readlane_b32 s48, v252, 38
	v_readlane_b32 s49, v252, 39
	v_readlane_b32 s50, v252, 40
	v_readlane_b32 s51, v252, 41
	v_readlane_b32 s54, v252, 44
	v_readlane_b32 s55, v252, 45
	v_readlane_b32 s56, v252, 46
	v_readlane_b32 s57, v252, 47
	v_readlane_b32 s58, v252, 48
	v_readlane_b32 s59, v252, 49
	s_cbranch_vccz .LBB0_395
	s_waitcnt vmcnt(14) lgkmcnt(0)
	v_mfma_f32_32x32x16_bf16 v[2:17], v[22:25], v[18:21], 0
	s_mov_b64 s[36:37], 0
